# v16 + NSA tile pairing so the two waves of a SIMD get one light and one heavy query tile (tile index w for waves 0-3, 11-w for waves 4-7)
# baseline (speedup 1.0000x reference)
; DI int tid_of(int wave_s) { unsigned z = 0; asm volatile("" : "+s"(z)); int l = __builtin_amdgcn_mbcnt_hi(~0u, __builtin_amdgcn_mbcnt_lo(~0u, z)); return wave_s * 64 + l; }
; DI int pi_row(int r) { return (r & 0x13) | ((r & 4) << 1) | ((r & 8) >> 1); }
; DI void nsa_phase(unsigned char* lds, KParamPtr P, int wv) {
;     ...
;   const int tid = tid_of(wv), lane = tid & 63, wave = tid >> 6, l31 = lane & 31, hh = lane >> 5;
;   unsigned char* selL = lds + LDS_WORK + wave * 512;
;   float* scw = (float*)(lds + LDS_WORK + 4096 + wave * 16384);
;   const bf16_t* proj = (const bf16_t*)(wsq + OFF_U + U_PROJ);
;   const bf16_t* vsT = (const bf16_t*)(wsq + OFF_U + U_VST);
;   const bf16_t* vwT = (const bf16_t*)(wsq + OFF_U + U_VWT);
;   const bf16_t* kc = (const bf16_t*)(wsq + OFF_MISC + MS_KC);
;   const bf16_t* vcT = (const bf16_t*)(wsq + OFF_MISC + MS_VCT);
;   float* part = (float*)(wsq + OFF_HB);
;   bf16_t* ao = (bf16_t*)(wsq + OFF_AO);
;   const int nw = gridDim.x * 8, gw = blockIdx.x * 8 + wave;
;   const int pr = pi_row(l31);
;   for (int it = gw; it < 2048; it += nw) {
;     const int blk_ = it >> 3, combo_ = blk_ & 7;
;     const int b = combo_ >> 1, g = combo_ & 1, tile = ((blk_ >> 3) << 3) + (it & 7), t0 = tile * 32, t = t0 + l31;
;     const size_t tok = (size_t)b * SEQ + t;
;     const bf16_t* kcb = kc + (size_t)((b * 2 + g) * 512) * 64;
;     const bf16_t* vcb = vcT + (size_t)((b * 2 + g) * 64) * 512;
; #pragma unroll 1
;     for (int x = 0; x < 64; ++x) scw[x * 64 + lane] = 0.f;
;     const int nkt = (2 * tile + 1 + 31) >> 5;
.LBB0_933:
	s_or_b64 exec, exec, s[4:5]
	s_mov_b64 s[4:5], s[64:65]
	s_barrier
	s_load_dwordx2 s[6:7], s[4:5], 0xc8
	s_mov_b32 s2, s89
	s_waitcnt lgkmcnt(0)
	v_readlane_b32 s4, v254, 0
	v_mbcnt_lo_u32_b32 v0, -1, s2
	v_mbcnt_hi_u32_b32 v4, -1, v0
	v_add_u32_e32 v3, s4, v4
	v_ashrrev_i32_e32 v2, 6, v3
	v_readlane_b32 s2, v254, 33
	v_readlane_b32 s5, v254, 1
	s_nop 0
	v_add_u32_e32 v165, s2, v2
	s_movk_i32 s2, 0x800
	v_cmp_gt_i32_e32 vcc, s2, v165
	s_and_saveexec_b64 s[18:19], vcc
	s_cbranch_execz .LBB0_1158
	v_lshlrev_b32_e32 v6, 1, v4
	v_lshrrev_b32_e32 v8, 1, v4
	v_lshl_add_u32 v164, v2, 9, 0
	v_and_b32_e32 v0, 19, v4
	v_and_b32_e32 v6, 8, v6
	v_and_b32_e32 v7, 4, v8
	s_movk_i32 s2, 0x3e00
	v_and_b32_e32 v5, 63, v4
	s_add_u32 s20, s6, 0x8000000
	v_or3_b32 v224, v7, v0, v6
	v_mad_u64_u32 v[6:7], s[4:5], v2, s2, v[164:165]
	v_and_b32_e32 v222, 31, v4
	v_bfe_u32 v223, v4, 5, 1
	s_addc_u32 s21, s7, 0
	v_lshlrev_b32_e32 v7, 2, v5
	v_cmp_gt_u32_e64 s[4:5], 32, v5
	v_and_b32_e32 v11, 15, v4
	v_bfe_u32 v229, v4, 2, 2
	v_and_b32_e32 v230, 3, v4
	v_and_b32_e32 v170, 24, v8
	v_mov_b32_e32 v171, v1
	v_and_b32_e32 v4, 48, v4
	v_mov_b32_e32 v5, v1
	v_lshlrev_b32_e32 v0, 4, v223
	v_lshl_add_u64 v[172:173], s[20:21], 0, v[4:5]
	v_lshl_add_u64 v[174:175], s[6:7], 0, v[4:5]
	v_lshl_add_u64 v[4:5], s[6:7], 0, v[170:171]
	s_mov_b64 s[8:9], 0x4000000
	v_lshl_add_u64 v[176:177], v[4:5], 0, s[8:9]
	v_lshl_or_b32 v4, v224, 7, v0
	v_mov_b32_e32 v5, v1
	s_add_u32 s22, s6, 0x11e00000
	v_lshl_add_u64 v[166:167], s[20:21], 0, v[0:1]
	v_lshlrev_b32_e32 v10, 2, v222
	v_lshl_add_u64 v[168:169], s[6:7], 0, v[0:1]
	v_lshl_add_u64 v[4:5], s[6:7], 0, v[4:5]
	s_mov_b64 s[8:9], 0x1a600000
	v_lshl_or_b32 v0, v222, 10, v0
	s_addc_u32 s23, s7, 0
	v_add_u32_e32 v225, v6, v7
	v_add_u32_e32 v226, v6, v10
	v_lshlrev_b32_e32 v6, 8, v223
	v_bfe_u32 v171, v3, 6, 3
	v_bfe_i32 v9, v3, 8, 1
	v_and_b32_e32 v9, 3, v9
	v_xor_b32_e32 v171, v171, v9
	v_lshl_add_u64 v[178:179], v[4:5], 0, s[8:9]
	v_lshlrev_b32_e32 v3, 7, v223
	v_lshl_add_u64 v[4:5], s[6:7], 0, v[0:1]
	v_lshlrev_b32_e32 v0, 14, v2
	v_lshlrev_b32_e32 v9, 3, v223
	v_xor_b32_e32 v227, 0x80, v7
	v_lshlrev_b32_e32 v7, 4, v222
	v_sub_u32_e32 v234, v222, v3
	v_lshlrev_b32_e32 v3, 10, v171
	s_mov_b64 s[8:9], 0x1a708020
	v_or3_b32 v0, v0, v6, v10
	v_readlane_b32 s2, v255, 9
	s_add_u32 s24, s6, 0x12680020
	v_lshlrev_b32_e32 v228, 1, v223
	v_or_b32_e32 v232, 0x400, v9
	v_or_b32_e32 v233, 0x300, v170
	v_add_u32_e32 v235, 0xfffffdf1, v3
	v_lshl_add_u64 v[180:181], v[4:5], 0, s[8:9]
	v_add_u32_e32 v236, s2, v0
	v_or_b32_e32 v237, 31, v3
	v_sub_u32_e32 v238, v222, v9
	s_addc_u32 s25, s7, 0
	v_lshl_or_b32 v239, v222, 13, v9
	s_mov_b64 s[26:27], 0
	v_add_u32_e32 v240, v164, v7
	v_lshlrev_b32_e32 v241, 13, v11
	s_branch .LBB0_936
